# barrier trims + P1 weight-conversion loop: gains from LDS, counted vmcnt keeps the other tile's loads in flight
# speedup vs baseline: 1.0104x; 1.0062x over previous
.LBB0_551:
	s_mov_b64 s[16:17], -1
	s_andn2_b64 vcc, exec, s[88:89]
	s_mov_b64 s[2:3], -1
	s_cbranch_vccnz .LBB0_228
	v_readlane_b32 s2, v254, 45
	v_readlane_b32 s3, v254, 46
	s_andn2_b64 vcc, exec, s[2:3]
	v_mbcnt_lo_u32_b32 v136, -1, 0
	v_mbcnt_hi_u32_b32 v136, -1, v136
	s_cbranch_vccnz .LBB0_227
	s_load_dwordx2 s[98:99], s[0:1], 0x70
	v_readlane_b32 s100, v254, 4
	s_mov_b32 s101, 0
	s_nop 2
	v_add_lshl_u32 v242, v136, s100, 5
	s_mov_b32 s100, 0
	s_waitcnt lgkmcnt(0)
	global_load_dwordx4 v[244:247], v242, s[98:99]
	global_load_dwordx4 v[248:251], v242, s[98:99] offset:16
	v_add_u32_e32 v243, 0x11000, v242
	s_waitcnt vmcnt(0)
	ds_write_b128 v243, v[244:247]
	ds_write_b128 v243, v[248:251] offset:16
	s_waitcnt lgkmcnt(0)
	s_barrier
	v_readlane_b32 s2, v254, 32
	v_readlane_b32 s3, v254, 33
	s_andn2_b64 vcc, exec, s[2:3]
	s_cbranch_vccnz .LBB0_555
	s_load_dwordx2 s[4:5], s[0:1], 0x70
	v_readlane_b32 s6, v254, 52
	s_movk_i32 s39, 0x4000
	s_movk_i32 s42, 0x1000
	v_readlane_b32 s7, v254, 53
	s_mov_b64 s[2:3], s[24:25]
	v_readlane_b32 s33, v254, 34
	v_readlane_b32 s38, v254, 41
	s_branch .LBB0_556

.LBB0_592:
	s_or_b64 exec, exec, s[2:3]
	v_mov_b32_e32 v127, 0
	v_mov_b32_e32 v126, 0
	v_mov_b32_e32 v125, 0
	v_mov_b32_e32 v124, 0
	v_mov_b32_e32 v131, 0
	v_mov_b32_e32 v130, 0
	v_mov_b32_e32 v129, 0
	v_mov_b32_e32 v128, 0
	s_and_saveexec_b64 s[2:3], vcc
	s_cbranch_execz .LBB0_594
	s_mul_i32 s40, s49, 0xe0
	v_lshl_add_u64 v[2:3], v[134:135], 0, s[40:41]
	s_lshl_b32 s40, s49, 2
	v_lshl_add_u64 v[124:125], v[2:3], 0, s[40:41]
	global_load_dwordx4 v[128:131], v[2:3], off nt
	s_nop 0
	global_load_dwordx4 v[124:127], v[124:125], off nt
	s_mov_b32 s100, 1

.LBB0_599:
	s_lshl_b32 s14, s33, 6
	s_ashr_i32 s15, s14, 31
	s_cmp_lg_u64 s[4:5], 0
	v_mov_b32_e32 v2, 1.0
	s_cselect_b64 s[18:19], -1, 0
	s_cmp_eq_u64 s[4:5], 0
	v_mov_b32_e32 v138, 1.0
	v_mov_b32_e32 v139, 1.0
	s_cbranch_scc1 .LBB0_601
	s_lshl_b32 s2, s14, 2
	s_add_u32 s2, s2, 0x11000
	v_lshl_add_u32 v138, v134, 2, s2
	ds_read_b64 v[138:139], v138
.LBB0_601:
	s_cmp_eq_u32 s100, 1
	s_mov_b32 s100, 0
	s_cbranch_scc1 .Lconv_fast_a
	s_waitcnt vmcnt(0)
	s_branch .Lconv_go_a
.Lconv_fast_a:
	s_waitcnt vmcnt(16)
.Lconv_go_a:
	s_waitcnt lgkmcnt(0)
	v_mul_f32_e32 v1, v4, v138
	v_mul_f32_e32 v3, v8, v139
	v_cvt_pk_bf16_f32 v1, v1, v3
	ds_write_b32 v156, v1
	v_mul_f32_e32 v1, v5, v138
	v_mul_f32_e32 v3, v9, v139
	v_cvt_pk_bf16_f32 v1, v1, v3
	ds_write_b32 v156, v1 offset:132
	v_mul_f32_e32 v1, v6, v138
	v_mul_f32_e32 v3, v10, v139
	v_cvt_pk_bf16_f32 v1, v1, v3
	ds_write_b32 v156, v1 offset:264
	v_mul_f32_e32 v1, v7, v138
	v_mul_f32_e32 v3, v11, v139
	v_cvt_pk_bf16_f32 v1, v1, v3
	ds_write_b32 v156, v1 offset:396
	v_cndmask_b32_e64 v1, 0, 1, s[18:19]
	v_cmp_ne_u32_e64 s[2:3], 1, v1
	s_andn2_b64 vcc, exec, s[18:19]
	v_mov_b32_e32 v3, 1.0
	s_cbranch_vccnz .LBB0_603
	s_lshl_b32 s18, s14, 2
	s_add_u32 s18, s18, 0x11000
	v_lshl_add_u32 v2, v134, 2, s18
	ds_read_b64 v[2:3], v2 offset:32
.LBB0_603:
	s_waitcnt lgkmcnt(0)
	v_mul_f32_e32 v1, v12, v2
	v_mul_f32_e32 v133, v16, v3
	v_cvt_pk_bf16_f32 v1, v1, v133
	ds_write_b32 v156, v1 offset:16
	v_mul_f32_e32 v1, v13, v2
	v_mul_f32_e32 v133, v17, v3
	v_cvt_pk_bf16_f32 v1, v1, v133
	ds_write_b32 v156, v1 offset:148
	v_mul_f32_e32 v1, v14, v2
	v_mul_f32_e32 v133, v18, v3
	v_cvt_pk_bf16_f32 v1, v1, v133
	ds_write_b32 v156, v1 offset:280
	v_mul_f32_e32 v1, v15, v2
	v_mul_f32_e32 v2, v19, v3
	v_cvt_pk_bf16_f32 v1, v1, v2
	v_mov_b32_e32 v2, 1.0
	s_and_b64 vcc, exec, s[2:3]
	v_mov_b32_e32 v138, 1.0
	v_mov_b32_e32 v139, 1.0
	ds_write_b32 v156, v1 offset:412
	s_cbranch_vccnz .LBB0_605
	s_lshl_b32 s18, s14, 2
	s_add_u32 s18, s18, 0x11000
	v_lshl_add_u32 v138, v134, 2, s18
	ds_read_b64 v[138:139], v138 offset:64
.LBB0_605:
	s_waitcnt lgkmcnt(0)
	v_mul_f32_e32 v1, v20, v138
	v_mul_f32_e32 v3, v24, v139
	v_cvt_pk_bf16_f32 v1, v1, v3
	ds_write_b32 v156, v1 offset:32
	v_mul_f32_e32 v1, v21, v138
	v_mul_f32_e32 v3, v25, v139
	v_cvt_pk_bf16_f32 v1, v1, v3
	ds_write_b32 v156, v1 offset:164
	v_mul_f32_e32 v1, v22, v138
	v_mul_f32_e32 v3, v26, v139
	v_cvt_pk_bf16_f32 v1, v1, v3
	ds_write_b32 v156, v1 offset:296
	v_mul_f32_e32 v1, v23, v138
	v_mul_f32_e32 v3, v27, v139
	v_cvt_pk_bf16_f32 v1, v1, v3
	s_and_b64 vcc, exec, s[2:3]
	v_mov_b32_e32 v3, 1.0
	ds_write_b32 v156, v1 offset:428
	s_cbranch_vccnz .LBB0_607
	s_lshl_b32 s18, s14, 2
	s_add_u32 s18, s18, 0x11000
	v_lshl_add_u32 v2, v134, 2, s18
	ds_read_b64 v[2:3], v2 offset:96
.LBB0_607:
	s_waitcnt lgkmcnt(0)
	v_mul_f32_e32 v1, v28, v2
	v_mul_f32_e32 v133, v32, v3
	v_cvt_pk_bf16_f32 v1, v1, v133
	ds_write_b32 v156, v1 offset:48
	v_mul_f32_e32 v1, v29, v2
	v_mul_f32_e32 v133, v33, v3
	v_cvt_pk_bf16_f32 v1, v1, v133
	ds_write_b32 v156, v1 offset:180
	v_mul_f32_e32 v1, v30, v2
	v_mul_f32_e32 v133, v34, v3
	v_cvt_pk_bf16_f32 v1, v1, v133
	ds_write_b32 v156, v1 offset:312
	v_mul_f32_e32 v1, v31, v2
	v_mul_f32_e32 v2, v35, v3
	v_cvt_pk_bf16_f32 v1, v1, v2
	v_mov_b32_e32 v2, 1.0
	s_and_b64 vcc, exec, s[2:3]
	v_mov_b32_e32 v138, 1.0
	v_mov_b32_e32 v139, 1.0
	ds_write_b32 v156, v1 offset:444
	s_cbranch_vccnz .LBB0_609
	s_lshl_b32 s18, s14, 2
	s_add_u32 s18, s18, 0x11000
	v_lshl_add_u32 v138, v134, 2, s18
	ds_read_b64 v[138:139], v138 offset:128
.LBB0_609:
	s_waitcnt lgkmcnt(0)
	v_mul_f32_e32 v1, v36, v138
	v_mul_f32_e32 v3, v40, v139
	v_cvt_pk_bf16_f32 v1, v1, v3
	ds_write_b32 v156, v1 offset:64
	v_mul_f32_e32 v1, v37, v138
	v_mul_f32_e32 v3, v41, v139
	v_cvt_pk_bf16_f32 v1, v1, v3
	ds_write_b32 v156, v1 offset:196
	v_mul_f32_e32 v1, v38, v138
	v_mul_f32_e32 v3, v42, v139
	v_cvt_pk_bf16_f32 v1, v1, v3
	ds_write_b32 v156, v1 offset:328
	v_mul_f32_e32 v1, v39, v138
	v_mul_f32_e32 v3, v43, v139
	v_cvt_pk_bf16_f32 v1, v1, v3
	s_and_b64 vcc, exec, s[2:3]
	v_mov_b32_e32 v3, 1.0
	ds_write_b32 v156, v1 offset:460
	s_cbranch_vccnz .LBB0_611
	s_lshl_b32 s18, s14, 2
	s_add_u32 s18, s18, 0x11000
	v_lshl_add_u32 v2, v134, 2, s18
	ds_read_b64 v[2:3], v2 offset:160
.LBB0_611:
	s_waitcnt lgkmcnt(0)
	v_mul_f32_e32 v1, v60, v2
	v_mul_f32_e32 v133, v64, v3
	v_cvt_pk_bf16_f32 v1, v1, v133
	ds_write_b32 v156, v1 offset:80
	v_mul_f32_e32 v1, v61, v2
	v_mul_f32_e32 v133, v65, v3
	v_cvt_pk_bf16_f32 v1, v1, v133
	ds_write_b32 v156, v1 offset:212
	v_mul_f32_e32 v1, v62, v2
	v_mul_f32_e32 v133, v66, v3
	v_cvt_pk_bf16_f32 v1, v1, v133
	ds_write_b32 v156, v1 offset:344
	v_mul_f32_e32 v1, v63, v2
	v_mul_f32_e32 v2, v67, v3
	v_cvt_pk_bf16_f32 v1, v1, v2
	v_mov_b32_e32 v2, 1.0
	s_and_b64 vcc, exec, s[2:3]
	v_mov_b32_e32 v138, 1.0
	v_mov_b32_e32 v139, 1.0
	ds_write_b32 v156, v1 offset:476
	s_cbranch_vccnz .LBB0_613
	s_lshl_b32 s18, s14, 2
	s_add_u32 s18, s18, 0x11000
	v_lshl_add_u32 v138, v134, 2, s18
	ds_read_b64 v[138:139], v138 offset:192
.LBB0_613:
	s_waitcnt lgkmcnt(0)
	v_mul_f32_e32 v1, v84, v138
	v_mul_f32_e32 v3, v88, v139
	v_cvt_pk_bf16_f32 v1, v1, v3
	ds_write_b32 v156, v1 offset:96
	v_mul_f32_e32 v1, v85, v138
	v_mul_f32_e32 v3, v89, v139
	v_cvt_pk_bf16_f32 v1, v1, v3
	ds_write_b32 v156, v1 offset:228
	v_mul_f32_e32 v1, v86, v138
	v_mul_f32_e32 v3, v90, v139
	v_cvt_pk_bf16_f32 v1, v1, v3
	ds_write_b32 v156, v1 offset:360
	v_mul_f32_e32 v1, v87, v138
	v_mul_f32_e32 v3, v91, v139
	v_cvt_pk_bf16_f32 v1, v1, v3
	s_and_b64 vcc, exec, s[2:3]
	v_mov_b32_e32 v3, 1.0
	ds_write_b32 v156, v1 offset:492
	s_cbranch_vccnz .LBB0_615
	s_lshl_b32 s2, s14, 2
	s_add_u32 s2, s2, 0x11000
	v_lshl_add_u32 v2, v134, 2, s2
	ds_read_b64 v[2:3], v2 offset:224
.LBB0_615:
	s_waitcnt lgkmcnt(0)
	v_mul_f32_e32 v1, v108, v2
	v_mul_f32_e32 v133, v112, v3
	v_cvt_pk_bf16_f32 v1, v1, v133
	ds_write_b32 v156, v1 offset:112
	v_mul_f32_e32 v1, v109, v2
	v_mul_f32_e32 v133, v113, v3
	v_cvt_pk_bf16_f32 v1, v1, v133
	ds_write_b32 v156, v1 offset:244
	v_mul_f32_e32 v1, v110, v2
	v_mul_f32_e32 v133, v114, v3
	v_cvt_pk_bf16_f32 v1, v1, v133
	ds_write_b32 v156, v1 offset:376
	v_mul_f32_e32 v1, v111, v2
	v_mul_f32_e32 v2, v115, v3
	v_cvt_pk_bf16_f32 v1, v1, v2
	s_lshl_b32 s18, s38, 6
	ds_write_b32 v156, v1 offset:508
	v_add_u32_e32 v1, s18, v142
	v_cmp_gt_i32_e32 vcc, s39, v1
	v_lshlrev_b32_e32 v138, 1, v136
	s_and_saveexec_b64 s[2:3], vcc
	s_cbranch_execz .LBB0_617
	v_mad_u64_u32 v[2:3], s[34:35], s42, v1, 0
	v_ashrrev_i32_e32 v133, 31, v1
	v_mov_b32_e32 v140, v3
	ds_read2_b32 v[158:159], v157 offset1:1
	ds_read2_b32 v[160:161], v157 offset0:2 offset1:3
	v_mad_u64_u32 v[140:141], s[34:35], s42, v133, v[140:141]
	v_mov_b32_e32 v3, v140
	v_lshl_add_u64 v[2:3], v[2:3], 1, s[6:7]
	v_lshl_add_u64 v[2:3], s[14:15], 1, v[2:3]
	v_mov_b32_e32 v139, v0
	v_lshl_add_u64 v[2:3], v[2:3], 0, v[138:139]
	s_waitcnt lgkmcnt(0)
	global_store_dwordx4 v[2:3], v[158:161], off nt

.LBB0_637:
	s_lshl_b32 s12, s43, 6
	s_ashr_i32 s13, s12, 31
	s_cmp_lg_u64 s[8:9], 0
	v_mov_b32_e32 v2, 1.0
	s_cselect_b64 s[18:19], -1, 0
	s_cmp_eq_u64 s[8:9], 0
	v_mov_b32_e32 v140, 1.0
	v_mov_b32_e32 v141, 1.0
	s_cbranch_scc1 .LBB0_639
	s_lshl_b32 s2, s12, 2
	s_add_u32 s2, s2, 0x11000
	v_lshl_add_u32 v140, v134, 2, s2
	ds_read_b64 v[140:141], v140
.LBB0_639:
	s_cmp_eq_u32 s101, 1
	s_mov_b32 s101, 0
	s_cbranch_scc1 .Lconv_fast_b
	s_waitcnt vmcnt(0)
	s_branch .Lconv_go_b
.Lconv_fast_b:
	s_waitcnt vmcnt(24)
.Lconv_go_b:
	s_waitcnt lgkmcnt(0)
	v_mul_f32_e32 v1, v48, v140
	v_mul_f32_e32 v3, v44, v141
	v_cvt_pk_bf16_f32 v1, v1, v3
	ds_write_b32 v156, v1
	v_mul_f32_e32 v1, v49, v140
	v_mul_f32_e32 v3, v45, v141
	v_cvt_pk_bf16_f32 v1, v1, v3
	ds_write_b32 v156, v1 offset:132
	v_mul_f32_e32 v1, v50, v140
	v_mul_f32_e32 v3, v46, v141
	v_cvt_pk_bf16_f32 v1, v1, v3
	ds_write_b32 v156, v1 offset:264
	v_mul_f32_e32 v1, v51, v140
	v_mul_f32_e32 v3, v47, v141
	v_cvt_pk_bf16_f32 v1, v1, v3
	ds_write_b32 v156, v1 offset:396
	v_cndmask_b32_e64 v1, 0, 1, s[18:19]
	v_cmp_ne_u32_e64 s[2:3], 1, v1
	s_andn2_b64 vcc, exec, s[18:19]
	v_mov_b32_e32 v3, 1.0
	s_cbranch_vccnz .LBB0_641
	s_lshl_b32 s18, s12, 2
	s_add_u32 s18, s18, 0x11000
	v_lshl_add_u32 v2, v134, 2, s18
	ds_read_b64 v[2:3], v2 offset:32
.LBB0_641:
	s_waitcnt lgkmcnt(0)
	v_mul_f32_e32 v1, v56, v2
	v_mul_f32_e32 v133, v52, v3
	v_cvt_pk_bf16_f32 v1, v1, v133
	ds_write_b32 v156, v1 offset:16
	v_mul_f32_e32 v1, v57, v2
	v_mul_f32_e32 v133, v53, v3
	v_cvt_pk_bf16_f32 v1, v1, v133
	ds_write_b32 v156, v1 offset:148
	v_mul_f32_e32 v1, v58, v2
	v_mul_f32_e32 v133, v54, v3
	v_cvt_pk_bf16_f32 v1, v1, v133
	ds_write_b32 v156, v1 offset:280
	v_mul_f32_e32 v1, v59, v2
	v_mul_f32_e32 v2, v55, v3
	v_cvt_pk_bf16_f32 v1, v1, v2
	v_mov_b32_e32 v2, 1.0
	s_and_b64 vcc, exec, s[2:3]
	v_mov_b32_e32 v140, 1.0
	v_mov_b32_e32 v141, 1.0
	ds_write_b32 v156, v1 offset:412
	s_cbranch_vccnz .LBB0_643
	s_lshl_b32 s18, s12, 2
	s_add_u32 s18, s18, 0x11000
	v_lshl_add_u32 v140, v134, 2, s18
	ds_read_b64 v[140:141], v140 offset:64
.LBB0_643:
	s_waitcnt lgkmcnt(0)
	v_mul_f32_e32 v1, v72, v140
	v_mul_f32_e32 v3, v68, v141
	v_cvt_pk_bf16_f32 v1, v1, v3
	ds_write_b32 v156, v1 offset:32
	v_mul_f32_e32 v1, v73, v140
	v_mul_f32_e32 v3, v69, v141
	v_cvt_pk_bf16_f32 v1, v1, v3
	ds_write_b32 v156, v1 offset:164
	v_mul_f32_e32 v1, v74, v140
	v_mul_f32_e32 v3, v70, v141
	v_cvt_pk_bf16_f32 v1, v1, v3
	ds_write_b32 v156, v1 offset:296
	v_mul_f32_e32 v1, v75, v140
	v_mul_f32_e32 v3, v71, v141
	v_cvt_pk_bf16_f32 v1, v1, v3
	s_and_b64 vcc, exec, s[2:3]
	v_mov_b32_e32 v3, 1.0
	ds_write_b32 v156, v1 offset:428
	s_cbranch_vccnz .LBB0_645
	s_lshl_b32 s18, s12, 2
	s_add_u32 s18, s18, 0x11000
	v_lshl_add_u32 v2, v134, 2, s18
	ds_read_b64 v[2:3], v2 offset:96
.LBB0_645:
	s_waitcnt lgkmcnt(0)
	v_mul_f32_e32 v1, v80, v2
	v_mul_f32_e32 v133, v76, v3
	v_cvt_pk_bf16_f32 v1, v1, v133
	ds_write_b32 v156, v1 offset:48
	v_mul_f32_e32 v1, v81, v2
	v_mul_f32_e32 v133, v77, v3
	v_cvt_pk_bf16_f32 v1, v1, v133
	ds_write_b32 v156, v1 offset:180
	v_mul_f32_e32 v1, v82, v2
	v_mul_f32_e32 v133, v78, v3
	v_cvt_pk_bf16_f32 v1, v1, v133
	ds_write_b32 v156, v1 offset:312
	v_mul_f32_e32 v1, v83, v2
	v_mul_f32_e32 v2, v79, v3
	v_cvt_pk_bf16_f32 v1, v1, v2
	v_mov_b32_e32 v2, 1.0
	s_and_b64 vcc, exec, s[2:3]
	v_mov_b32_e32 v140, 1.0
	v_mov_b32_e32 v141, 1.0
	ds_write_b32 v156, v1 offset:444
	s_cbranch_vccnz .LBB0_647
	s_lshl_b32 s18, s12, 2
	s_add_u32 s18, s18, 0x11000
	v_lshl_add_u32 v140, v134, 2, s18
	ds_read_b64 v[140:141], v140 offset:128
.LBB0_647:
	s_waitcnt lgkmcnt(0)
	v_mul_f32_e32 v1, v96, v140
	v_mul_f32_e32 v3, v92, v141
	v_cvt_pk_bf16_f32 v1, v1, v3
	ds_write_b32 v156, v1 offset:64
	v_mul_f32_e32 v1, v97, v140
	v_mul_f32_e32 v3, v93, v141
	v_cvt_pk_bf16_f32 v1, v1, v3
	ds_write_b32 v156, v1 offset:196
	v_mul_f32_e32 v1, v98, v140
	v_mul_f32_e32 v3, v94, v141
	v_cvt_pk_bf16_f32 v1, v1, v3
	ds_write_b32 v156, v1 offset:328
	v_mul_f32_e32 v1, v99, v140
	v_mul_f32_e32 v3, v95, v141
	v_cvt_pk_bf16_f32 v1, v1, v3
	s_and_b64 vcc, exec, s[2:3]
	v_mov_b32_e32 v3, 1.0
	ds_write_b32 v156, v1 offset:460
	s_cbranch_vccnz .LBB0_649
	s_lshl_b32 s18, s12, 2
	s_add_u32 s18, s18, 0x11000
	v_lshl_add_u32 v2, v134, 2, s18
	ds_read_b64 v[2:3], v2 offset:160
.LBB0_649:
	s_waitcnt lgkmcnt(0)
	v_mul_f32_e32 v1, v104, v2
	v_mul_f32_e32 v133, v100, v3
	v_cvt_pk_bf16_f32 v1, v1, v133
	ds_write_b32 v156, v1 offset:80
	v_mul_f32_e32 v1, v105, v2
	v_mul_f32_e32 v133, v101, v3
	v_cvt_pk_bf16_f32 v1, v1, v133
	ds_write_b32 v156, v1 offset:212
	v_mul_f32_e32 v1, v106, v2
	v_mul_f32_e32 v133, v102, v3
	v_cvt_pk_bf16_f32 v1, v1, v133
	ds_write_b32 v156, v1 offset:344
	v_mul_f32_e32 v1, v107, v2
	v_mul_f32_e32 v2, v103, v3
	v_cvt_pk_bf16_f32 v1, v1, v2
	v_mov_b32_e32 v2, 1.0
	s_and_b64 vcc, exec, s[2:3]
	v_mov_b32_e32 v140, 1.0
	v_mov_b32_e32 v141, 1.0
	ds_write_b32 v156, v1 offset:476
	s_cbranch_vccnz .LBB0_651
	s_lshl_b32 s18, s12, 2
	s_add_u32 s18, s18, 0x11000
	v_lshl_add_u32 v140, v134, 2, s18
	ds_read_b64 v[140:141], v140 offset:192
.LBB0_651:
	s_waitcnt lgkmcnt(0)
	v_mul_f32_e32 v1, v120, v140
	v_mul_f32_e32 v3, v116, v141
	v_cvt_pk_bf16_f32 v1, v1, v3
	ds_write_b32 v156, v1 offset:96
	v_mul_f32_e32 v1, v121, v140
	v_mul_f32_e32 v3, v117, v141
	v_cvt_pk_bf16_f32 v1, v1, v3
	ds_write_b32 v156, v1 offset:228
	v_mul_f32_e32 v1, v122, v140
	v_mul_f32_e32 v3, v118, v141
	v_cvt_pk_bf16_f32 v1, v1, v3
	ds_write_b32 v156, v1 offset:360
	v_mul_f32_e32 v1, v123, v140
	v_mul_f32_e32 v3, v119, v141
	v_cvt_pk_bf16_f32 v1, v1, v3
	s_and_b64 vcc, exec, s[2:3]
	v_mov_b32_e32 v3, 1.0
	ds_write_b32 v156, v1 offset:492
	s_cbranch_vccnz .LBB0_653
	s_lshl_b32 s2, s12, 2
	s_add_u32 s2, s2, 0x11000
	v_lshl_add_u32 v2, v134, 2, s2
	ds_read_b64 v[2:3], v2 offset:224
.LBB0_653:
	s_waitcnt lgkmcnt(0)
	v_mul_f32_e32 v1, v128, v2
	v_mul_f32_e32 v133, v124, v3
	v_cvt_pk_bf16_f32 v1, v1, v133
	ds_write_b32 v156, v1 offset:112
	v_mul_f32_e32 v1, v129, v2
	v_mul_f32_e32 v133, v125, v3
	v_cvt_pk_bf16_f32 v1, v1, v133
	ds_write_b32 v156, v1 offset:244
	v_mul_f32_e32 v1, v130, v2
	v_mul_f32_e32 v133, v126, v3
	v_cvt_pk_bf16_f32 v1, v1, v133
	ds_write_b32 v156, v1 offset:376
	v_mul_f32_e32 v1, v131, v2
	v_mul_f32_e32 v2, v127, v3
	v_cvt_pk_bf16_f32 v1, v1, v2
	s_lshl_b32 s18, s48, 6
	ds_write_b32 v156, v1 offset:508
	v_add_u32_e32 v1, s18, v142
	v_cmp_gt_i32_e32 vcc, s49, v1
	s_and_saveexec_b64 s[2:3], vcc
	s_cbranch_execz .LBB0_655
	v_mad_u64_u32 v[2:3], s[34:35], s52, v1, 0
	v_ashrrev_i32_e32 v133, 31, v1
	v_mov_b32_e32 v140, v3
	ds_read2_b32 v[158:159], v157 offset1:1
	ds_read2_b32 v[160:161], v157 offset0:2 offset1:3
	v_mad_u64_u32 v[140:141], s[34:35], s52, v133, v[140:141]
	v_mov_b32_e32 v3, v140
	v_lshl_add_u64 v[2:3], v[2:3], 1, s[10:11]
	v_lshl_add_u64 v[2:3], s[12:13], 1, v[2:3]
	v_mov_b32_e32 v139, v0
	v_lshl_add_u64 v[2:3], v[2:3], 0, v[138:139]
	s_waitcnt lgkmcnt(0)
	global_store_dwordx4 v[2:3], v[158:161], off nt

.LBB0_685:
	s_or_b64 exec, exec, s[2:3]
	s_and_saveexec_b64 s[2:3], vcc
	s_xor_b64 s[2:3], exec, s[2:3]
	s_or_saveexec_b64 s[2:3], s[2:3]
	v_mov_b32_e32 v111, 0
	v_mov_b32_e32 v110, 0
	v_mov_b32_e32 v109, 0
	v_mov_b32_e32 v108, 0
	v_mov_b32_e32 v115, 0
	v_mov_b32_e32 v114, 0
	v_mov_b32_e32 v113, 0
	v_mov_b32_e32 v112, 0
	s_xor_b64 exec, exec, s[2:3]
	s_cbranch_execz .LBB0_689
	s_mul_i32 s40, s39, 0xe0
	v_lshl_add_u64 v[2:3], v[140:141], 0, s[40:41]
	s_lshl_b32 s40, s39, 2
	v_lshl_add_u64 v[112:113], v[2:3], 0, s[40:41]
	global_load_dwordx4 v[108:111], v[2:3], off nt
	s_nop 0
	global_load_dwordx4 v[112:115], v[112:113], off nt
	s_mov_b32 s101, 1

.LBB0_711:
	s_or_b64 exec, exec, s[2:3]
	v_mov_b32_e32 v127, 0
	v_mov_b32_e32 v126, 0
	v_mov_b32_e32 v125, 0
	v_mov_b32_e32 v124, 0
	v_mov_b32_e32 v131, 0
	v_mov_b32_e32 v130, 0
	v_mov_b32_e32 v129, 0
	v_mov_b32_e32 v128, 0
	s_and_saveexec_b64 s[2:3], vcc
	s_cbranch_execz .LBB0_596
	s_mul_i32 s40, s49, 0xe0
	v_lshl_add_u64 v[2:3], v[138:139], 0, s[40:41]
	s_lshl_b32 s40, s49, 2
	v_lshl_add_u64 v[124:125], v[2:3], 0, s[40:41]
	global_load_dwordx4 v[128:131], v[2:3], off nt
	s_nop 0
	global_load_dwordx4 v[124:127], v[124:125], off nt
	s_mov_b32 s100, 1
	s_branch .LBB0_596
